# k4 plus double-buffered K fragment reads (counted lgkmcnt) in the mixer-B score-wave QK block
# speedup vs baseline: 1.0001x; 1.0001x over previous
; __device__ __forceinline__ void qkt(f32x16& p0, f32x16& p1, const char* Ks, const bf16x8* qr, int r32, int hi) {
;     p0 = f32x16{}; p1 = f32x16{};
; #pragma unroll
;     for (int d0 = 0; d0 < 8; ++d0) { const int cb = (d0 * 16 + hi * 8) * 2;
;         const bf16x8 b0 = *reinterpret_cast<const bf16x8*>(Ks + KSWZ(r32, cb));
;         const bf16x8 b1 = *reinterpret_cast<const bf16x8*>(Ks + KSWZ(32 + r32, cb));
;         p0 = __builtin_amdgcn_mfma_f32_32x32x16_bf16(b0, qr[d0], p0, 0, 0, 0);
;         p1 = __builtin_amdgcn_mfma_f32_32x32x16_bf16(b1, qr[d0], p1, 0, 0, 0); }
; __device__ __forceinline__ void attn_b2_unit(int b, int h, int qk, int jlo, const bf16_t* __restrict__ P, bf16_t* __restrict__ mix, const float* __restrict__ subg, float lam,
;                                              float* __restrict__ o0s, char* lds) {
;     ...
;                 if (s < T && j <= cwv) {
;                     f32x16 p0, p1;
;                     qkt(p0, p1, lds + B2_K + (s & 1) * 16384, qr, r32, hi);
;                     const int kb = 64 * j + 4 * hi;
; #pragma unroll
;                     for (int r = 0; r < 16; ++r) { const int rel = kb + (r & 3) + 8 * (r >> 2) - qp;
;                         p0[r] -= slope2 * fabsf((float)rel); p1[r] -= slope2 * fabsf((float)(rel + 32)); }
;                     float pmax = p0[0];
; #pragma unroll
;                     for (int r = 1; r < 16; ++r) pmax = fmaxf(pmax, p0[r]);
; #pragma unroll
;                     for (int r = 0; r < 16; ++r) pmax = fmaxf(pmax, p1[r]);
.LBB0_349:
	s_cmp_gt_i32 s3, s64
	s_cselect_b64 s[46:47], -1, 0
	s_or_b64 s[44:45], s[44:45], s[46:47]
	s_and_b64 vcc, exec, s[44:45]
	s_cbranch_vccnz .LBB0_353
	s_and_b32 s49, s2, 1
	s_lshl_b32 s48, s49, 14
	s_add_i32 s2, s48, 0
	s_add_i32 s2, s2, 0x10000
	v_add3_u32 v6, s2, v199, v183
	ds_read_b128 v[2:5], v6
	ds_read_b128 v[6:9], v6 offset:8192
	v_add3_u32 v72, s2, v200, v183
	ds_read_b128 v[68:71], v72
	ds_read_b128 v[72:75], v72 offset:8192
	v_add3_u32 v76, s2, v201, v183
	ds_read_b128 v[84:87], v76
	ds_read_b128 v[88:91], v76 offset:8192
	v_add3_u32 v76, s2, v202, v183
	s_waitcnt lgkmcnt(2)
	v_mfma_f32_32x32x16_bf16 v[18:33], v[2:5], v[34:37], 0
	v_mfma_f32_32x32x16_bf16 v[2:17], v[6:9], v[34:37], 0
	v_mfma_f32_32x32x16_bf16 v[2:17], v[72:75], v[38:41], v[2:17]
	v_mfma_f32_32x32x16_bf16 v[18:33], v[68:71], v[38:41], v[18:33]
	ds_read_b128 v[68:71], v76
	ds_read_b128 v[72:75], v76 offset:8192
	v_add3_u32 v76, s2, v203, v183
	s_waitcnt lgkmcnt(2)
	v_mfma_f32_32x32x16_bf16 v[2:17], v[88:91], v[42:45], v[2:17]
	v_mfma_f32_32x32x16_bf16 v[18:33], v[84:87], v[42:45], v[18:33]
	ds_read_b128 v[84:87], v76
	ds_read_b128 v[88:91], v76 offset:8192
	v_add3_u32 v76, s2, v204, v183
	s_waitcnt lgkmcnt(2)
	v_mfma_f32_32x32x16_bf16 v[2:17], v[72:75], v[46:49], v[2:17]
	v_mfma_f32_32x32x16_bf16 v[18:33], v[68:71], v[46:49], v[18:33]
	ds_read_b128 v[68:71], v76
	ds_read_b128 v[72:75], v76 offset:8192
	v_add3_u32 v76, s2, v205, v183
	s_waitcnt lgkmcnt(2)
	v_mfma_f32_32x32x16_bf16 v[2:17], v[88:91], v[50:53], v[2:17]
	v_mfma_f32_32x32x16_bf16 v[18:33], v[84:87], v[50:53], v[18:33]
	ds_read_b128 v[84:87], v76
	ds_read_b128 v[88:91], v76 offset:8192
	v_add3_u32 v76, s2, v206, v183
	s_mov_b32 s2, 0x41000000
	s_waitcnt lgkmcnt(2)
	v_mfma_f32_32x32x16_bf16 v[2:17], v[72:75], v[54:57], v[2:17]
	v_mfma_f32_32x32x16_bf16 v[18:33], v[68:71], v[54:57], v[18:33]
	ds_read_b128 v[68:71], v76
	ds_read_b128 v[72:75], v76 offset:8192
	v_subrev_u32_e32 v76, 59, v66
	v_cvt_f32_i32_e32 v76, v76
	s_waitcnt lgkmcnt(2)
	v_mfma_f32_32x32x16_bf16 v[2:17], v[88:91], v[58:61], v[2:17]
	v_mfma_f32_32x32x16_bf16 v[18:33], v[84:87], v[58:61], v[18:33]
	s_waitcnt lgkmcnt(0)
	v_mfma_f32_32x32x16_bf16 v[2:17], v[72:75], v[62:65], v[2:17]
	v_mfma_f32_32x32x16_bf16 v[18:33], v[68:71], v[62:65], v[18:33]
	v_subrev_u32_e32 v68, 27, v66
	v_cvt_f32_i32_e32 v68, v68
	v_subrev_u32_e32 v71, 24, v66
	v_subrev_u32_e32 v70, 26, v66
	v_cvt_f32_i32_e32 v71, v71
	s_nop 5
	v_fma_f32 v2, -v167, |v68|, v2
	v_subrev_u32_e32 v68, 57, v66
	v_cvt_f32_i32_e32 v68, v68
	v_cvt_f32_i32_e32 v70, v70
	v_subrev_u32_e32 v69, 58, v66
	v_cvt_f32_i32_e32 v69, v69
	v_fma_f32 v20, -v167, |v68|, v20
	v_fma_f32 v68, -v167, |v71|, v5
	v_subrev_u32_e32 v5, 51, v66
	v_fma_f32 v3, -v167, |v70|, v3
	v_subrev_u32_e32 v70, 56, v66
	v_cvt_f32_i32_e32 v5, v5
	v_cvt_f32_i32_e32 v70, v70
	v_subrev_u32_e32 v71, 18, v66
	v_cvt_f32_i32_e32 v71, v71
	v_fma_f32 v22, -v167, |v5|, v22
	v_subrev_u32_e32 v5, 49, v66
	v_fma_f32 v21, -v167, |v70|, v21
	v_subrev_u32_e32 v70, 50, v66
	v_cvt_f32_i32_e32 v5, v5
	v_cvt_f32_i32_e32 v70, v70
	v_fma_f32 v19, -v167, |v69|, v19
	v_subrev_u32_e32 v69, 25, v66
	v_cvt_f32_i32_e32 v69, v69
	v_fma_f32 v24, -v167, |v5|, v24
	v_subrev_u32_e32 v5, 43, v66
	v_fma_f32 v23, -v167, |v70|, v23
	v_fma_f32 v70, -v167, |v71|, v7
	v_subrev_u32_e32 v7, 48, v66
	v_cvt_f32_i32_e32 v5, v5
	v_cvt_f32_i32_e32 v7, v7
	v_fma_f32 v4, -v167, |v69|, v4
	v_subrev_u32_e32 v69, 19, v66
	v_cvt_f32_i32_e32 v69, v69
	v_fma_f32 v26, -v167, |v5|, v26
	v_subrev_u32_e32 v5, 41, v66
	v_fma_f32 v25, -v167, |v7|, v25
	v_subrev_u32_e32 v7, 42, v66
	v_cvt_f32_i32_e32 v5, v5
	v_cvt_f32_i32_e32 v7, v7
	v_fma_f32 v69, -v167, |v69|, v6
	v_subrev_u32_e32 v6, 17, v66
	v_cvt_f32_i32_e32 v6, v6
	v_fma_f32 v28, -v167, |v5|, v28
	v_subrev_u32_e32 v5, 35, v66
	v_fma_f32 v27, -v167, |v7|, v27
	v_subrev_u32_e32 v7, 40, v66
	v_cvt_f32_i32_e32 v5, v5
	v_cvt_f32_i32_e32 v7, v7
	v_fma_f32 v72, -v167, |v6|, v8
	v_add_u32_e32 v6, -11, v66
	v_cvt_f32_i32_e32 v6, v6
	v_add_u32_e32 v8, -10, v66
	v_fma_f32 v30, -v167, |v5|, v30
	v_subrev_u32_e32 v5, 33, v66
	v_cvt_f32_i32_e32 v8, v8
	v_fma_f32 v29, -v167, |v7|, v29
	v_subrev_u32_e32 v7, 34, v66
	v_cvt_f32_i32_e32 v5, v5
	v_cvt_f32_i32_e32 v7, v7
	v_fma_f32 v18, -v167, |v76|, v18
	v_fma_f32 v73, -v167, |v6|, v10
	v_add_u32_e32 v6, -9, v66
	v_fma_f32 v74, -v167, |v8|, v11
	v_cvt_f32_i32_e32 v6, v6
	v_add_u32_e32 v8, -8, v66
	v_fma_f32 v32, -v167, |v5|, v32
	v_max_f32_e32 v5, v18, v19
	v_cvt_f32_i32_e32 v8, v8
	v_fma_f32 v31, -v167, |v7|, v31
	v_subrev_u32_e32 v7, 32, v66
	v_max3_f32 v5, v5, v20, v21
	v_cvt_f32_i32_e32 v7, v7
	v_max3_f32 v5, v5, v22, v23
	v_max3_f32 v5, v5, v24, v25
	v_fma_f32 v75, -v167, |v6|, v12
	v_add_u32_e32 v6, -3, v66
	v_max3_f32 v5, v5, v26, v27
	v_add_u32_e32 v71, -16, v66
	v_fma_f32 v76, -v167, |v8|, v13
	v_cvt_f32_i32_e32 v6, v6
	v_add_u32_e32 v8, -2, v66
	v_max3_f32 v5, v5, v28, v29
; __device__ __forceinline__ void attn_b2_unit(int b, int h, int qk, int jlo, const bf16_t* __restrict__ P, bf16_t* __restrict__ mix, const float* __restrict__ subg, float lam,
;                                              float* __restrict__ o0s, char* lds) {
;     ...
;                     float pmax = p0[0];
; #pragma unroll
;                     for (int r = 1; r < 16; ++r) pmax = fmaxf(pmax, p0[r]);
; #pragma unroll
;                     for (int r = 0; r < 16; ++r) pmax = fmaxf(pmax, p1[r]);
;                     { auto rr = __builtin_amdgcn_permlane32_swap(__float_as_uint(pmax), __float_as_uint(pmax), false, false);
;                       pmax = fmaxf(__uint_as_float(rr[0]), __uint_as_float(rr[1])); }
;                     float mn, alpha;
;                     if (__all(pmax - m_reg <= THR2)) { mn = m_reg; alpha = 1.f; }
;                     else { mn = fmaxf(m_reg, pmax); alpha = __builtin_amdgcn_exp2f(m_reg - mn); m_reg = mn; }
;                     float ps = 0.f;
; #pragma unroll
;                     for (int r = 0; r < 16; ++r) { p0[r] = __builtin_amdgcn_exp2f(p0[r] - mn); p1[r] = __builtin_amdgcn_exp2f(p1[r] - mn); ps += p0[r] + p1[r]; }
;                     { auto rr = __builtin_amdgcn_permlane32_swap(__float_as_uint(ps), __float_as_uint(ps), false, false);
;                       ps = __uint_as_float(rr[0]) + __uint_as_float(rr[1]); }
;                     l_reg = l_reg * alpha + ps;
;                     if (hi == 0) *(float*)(lds + B2_A + (((s & 1) * 4 + sw) * 32 + r32) * 4) = alpha;
;                     bf16x8 pa0, pa1, pa2, pa3;
;                     PK4G(p0, 0, pa0); PK4G(p0, 8, pa1); PK4G(p1, 0, pa2); PK4G(p1, 8, pa3);
;                     char* pp = lds + B2_P + ((s & 1) * 4 + sw) * 4096 + lane * 16;
;                     *(bf16x8*)(pp) = pa0; *(bf16x8*)(pp + 1024) = pa1; *(bf16x8*)(pp + 2048) = pa2; *(bf16x8*)(pp + 3072) = pa3;
	v_cvt_f32_i32_e32 v71, v71
	v_cvt_f32_i32_e32 v8, v8
	v_fma_f32 v33, -v167, |v7|, v33
	v_max3_f32 v5, v5, v30, v31
	v_max3_f32 v5, v5, v32, v33
	v_max3_f32 v5, v5, v2, v3
	v_fma_f32 v77, -v167, |v6|, v14
	v_add_u32_e32 v6, -1, v66
	v_max3_f32 v5, v5, v4, v68
	v_fma_f32 v71, -v167, |v71|, v9
	v_fma_f32 v78, -v167, |v8|, v15
	v_cvt_f32_i32_e32 v6, v6
	v_cvt_f32_i32_e32 v8, v66
	v_max3_f32 v5, v5, v69, v70
	v_max3_f32 v5, v5, v72, v71
	v_max3_f32 v5, v5, v73, v74
	v_max3_f32 v5, v5, v75, v76
	v_fma_f32 v79, -v167, |v6|, v16
	v_fma_f32 v80, -v167, |v8|, v17
	v_max3_f32 v5, v5, v77, v78
	v_max3_f32 v5, v5, v79, v80
	v_mov_b32_e32 v6, v5
	s_nop 1
	v_permlane32_swap_b32_e32 v5, v6
	v_max_f32_e32 v6, v6, v6
	v_max_f32_e32 v5, v5, v5
	v_max_f32_e32 v5, v5, v6
	v_sub_f32_e32 v6, v5, v1
	v_cmp_ge_f32_e32 vcc, s2, v6
	s_cmp_eq_u64 vcc, exec
	v_max_f32_e32 v6, v1, v1
	v_max_f32_e32 v5, v6, v5
	s_cselect_b64 vcc, -1, 0
	v_sub_f32_e32 v6, v1, v5
	v_cndmask_b32_e32 v1, v5, v1, vcc
	v_sub_f32_e32 v5, v18, v1
	v_sub_f32_e32 v2, v2, v1
	v_exp_f32_e32 v5, v5
	v_exp_f32_e32 v2, v2
	v_sub_f32_e32 v7, v19, v1
	v_sub_f32_e32 v3, v3, v1
	v_exp_f32_e32 v81, v6
	v_add_f32_e32 v6, v5, v2
	v_exp_f32_e32 v7, v7
	v_exp_f32_e32 v3, v3
	v_add_f32_e32 v8, 0, v6
	v_sub_f32_e32 v6, v20, v1
	v_sub_f32_e32 v4, v4, v1
	v_exp_f32_e32 v9, v6
	v_exp_f32_e32 v4, v4
	v_add_f32_e32 v10, v7, v3
	v_sub_f32_e32 v6, v21, v1
	v_add_f32_e32 v8, v10, v8
	v_add_f32_e32 v10, v9, v4
	v_exp_f32_e32 v11, v6
	v_sub_f32_e32 v6, v68, v1
	v_add_f32_e32 v12, v10, v8
	v_sub_f32_e32 v8, v22, v1
	v_exp_f32_e32 v6, v6
	v_exp_f32_e32 v13, v8
	v_sub_f32_e32 v8, v69, v1
	v_exp_f32_e32 v8, v8
	v_add_f32_e32 v14, v11, v6
	v_sub_f32_e32 v10, v23, v1
	v_add_f32_e32 v12, v14, v12
	v_add_f32_e32 v14, v13, v8
	v_exp_f32_e32 v16, v10
	v_sub_f32_e32 v10, v70, v1
	v_add_f32_e32 v15, v14, v12
	v_sub_f32_e32 v12, v24, v1
	v_exp_f32_e32 v10, v10
	v_exp_f32_e32 v18, v12
	v_sub_f32_e32 v12, v72, v1
	v_exp_f32_e32 v12, v12
	v_add_f32_e32 v17, v16, v10
	v_sub_f32_e32 v14, v25, v1
	v_add_f32_e32 v15, v17, v15
	v_add_f32_e32 v17, v18, v12
	v_exp_f32_e32 v20, v14
	v_sub_f32_e32 v14, v71, v1
	v_add_f32_e32 v19, v17, v15
	v_sub_f32_e32 v15, v26, v1
	v_exp_f32_e32 v14, v14
	v_exp_f32_e32 v21, v15
	v_sub_f32_e32 v15, v73, v1
	v_exp_f32_e32 v15, v15
	v_add_f32_e32 v22, v20, v14
	v_sub_f32_e32 v17, v27, v1
	v_add_f32_e32 v19, v22, v19
	v_add_f32_e32 v22, v21, v15
	v_exp_f32_e32 v23, v17
	v_sub_f32_e32 v17, v74, v1
	v_add_f32_e32 v24, v22, v19
	v_sub_f32_e32 v19, v28, v1
	v_exp_f32_e32 v17, v17
	v_exp_f32_e32 v25, v19
	v_sub_f32_e32 v19, v75, v1
	v_exp_f32_e32 v19, v19
	v_add_f32_e32 v26, v23, v17
	v_sub_f32_e32 v22, v29, v1
	v_add_f32_e32 v24, v26, v24
	v_add_f32_e32 v26, v25, v19
	v_exp_f32_e32 v27, v22
	v_sub_f32_e32 v22, v76, v1
	v_add_f32_e32 v28, v26, v24
	v_sub_f32_e32 v24, v30, v1
	v_exp_f32_e32 v22, v22
	v_exp_f32_e32 v29, v24
	v_sub_f32_e32 v24, v77, v1
	v_exp_f32_e32 v24, v24
	v_add_f32_e32 v68, v27, v22
	v_sub_f32_e32 v26, v31, v1
	v_add_f32_e32 v28, v68, v28
	v_add_f32_e32 v30, v29, v24
	v_exp_f32_e32 v31, v26
	v_sub_f32_e32 v26, v78, v1
	v_add_f32_e32 v68, v30, v28
	v_sub_f32_e32 v28, v32, v1
	v_exp_f32_e32 v26, v26
	v_exp_f32_e32 v32, v28
	v_sub_f32_e32 v28, v79, v1
	v_sub_f32_e32 v30, v33, v1
	v_exp_f32_e32 v28, v28
	v_exp_f32_e32 v33, v30
	v_sub_f32_e32 v30, v80, v1
	v_exp_f32_e32 v30, v30
	v_add_f32_e32 v69, v31, v26
	v_add_f32_e32 v68, v69, v68
	v_add_f32_e32 v69, v32, v28
	v_add_f32_e32 v68, v69, v68
	v_add_f32_e32 v69, v33, v30
	v_add_f32_e32 v69, v69, v68
	v_mov_b32_e32 v70, v69
	v_cndmask_b32_e64 v68, v81, 1.0, vcc
	s_nop 0
	v_permlane32_swap_b32_e32 v69, v70
	s_and_saveexec_b64 s[44:45], s[6:7]
	v_lshl_or_b32 v71, s49, 9, v208
	v_add_u32_e32 v71, 0, v71
	v_add_u32_e32 v71, 0x20000, v71
	ds_write_b32 v71, v68
	s_or_b64 exec, exec, s[44:45]
	v_add_f32_e32 v76, v69, v70
	v_fmac_f32_e32 v76, v67, v68
	v_cvt_pk_bf16_f32 v68, v5, v7
	v_cvt_pk_bf16_f32 v69, v9, v11
	v_cvt_pk_bf16_f32 v70, v13, v16
	v_cvt_pk_bf16_f32 v71, v18, v20
	v_cvt_pk_bf16_f32 v72, v21, v23
	v_cvt_pk_bf16_f32 v73, v25, v27
	v_cvt_pk_bf16_f32 v74, v29, v31
	v_cvt_pk_bf16_f32 v75, v32, v33
	s_nop 0
	v_permlane32_swap_b32_e32 v68, v70
	v_permlane32_swap_b32_e32 v69, v71
	v_cvt_pk_bf16_f32 v2, v2, v3
	v_cvt_pk_bf16_f32 v3, v4, v6
	v_cvt_pk_bf16_f32 v4, v8, v10
	v_cvt_pk_bf16_f32 v5, v12, v14
	v_cvt_pk_bf16_f32 v6, v15, v17
	v_cvt_pk_bf16_f32 v7, v19, v22
	v_cvt_pk_bf16_f32 v8, v24, v26
	v_cvt_pk_bf16_f32 v9, v28, v30
	v_add_u32_e32 v10, s48, v207
	v_mov_b32_e32 v67, v76
	v_permlane32_swap_b32_e32 v72, v74
	v_permlane32_swap_b32_e32 v73, v75
	v_permlane32_swap_b32_e32 v2, v4
	v_permlane32_swap_b32_e32 v3, v5
	v_permlane32_swap_b32_e32 v6, v8
	v_permlane32_swap_b32_e32 v7, v9
	ds_write_b128 v10, v[68:71]
	ds_write_b128 v10, v[72:75] offset:1024
	ds_write_b128 v10, v[2:5] offset:2048
	ds_write_b128 v10, v[6:9] offset:3072
